# importance tables zeroed with five 16-byte LDS stores per thread instead of a 17-iteration loop
# baseline (speedup 1.0000x reference)
; #define LAS __attribute__((address_space(3)))
; __device__ __forceinline__ void attn_unit(unsigned char* ws, LAS unsigned char* lds, int b, int g, int c, const int tid) {
;     const int lane = tid & 63, w = tid >> 6, col = lane & 31, h = lane >> 5, r = col >> 3, qi = col & 7;
;     const int q = 8 * w + qi, t = 64 * c + q, head = g * 4 + r;
;     const size_t row = (size_t)b * SEQ + t;
;     const float slope2 = exp2f(-(float)(head + 1)) * LOG2E;
;     const bf16_t* Qp = (const bf16_t*)(ws + WS_Q) + row * 512 + head * 64 + 8 * h;
;     bf16x8 qf[4];
; #pragma unroll
;     for (int kk = 0; kk < 4; ++kk) qf[kk] = *(const bf16x8*)(Qp + 16 * kk);
;     for (int i = tid; i < 2 * 64 * IMPP; i += 512) ((LAS float*)(lds + A_IMPA))[i] = 0.f;
;     LAS float* outl = (LAS float*)(lds + A_OUT) + tid;
;     const size_t boff = (size_t)b * SEQ * 128 + g * 64;
;     const int nvalid = 4 * c + 3 > 255 ? 255 : 4 * c + 3;
;     const int nkb = (nvalid + 63) >> 6;
;     const unsigned long long cmpmask = (nkb >= 64) ? ~0ull : ((1ull << nkb) - 1ull);
;     const bf16_t* KCp = (const bf16_t*)(ws + WS_KC) + (size_t)b * 256 * 128 + g * 64;
;     const bf16_t* VCp = (const bf16_t*)(ws + WS_VC) + (size_t)b * 256 * 128 + g * 64;
.LBB0_142:
	s_and_b32 s68, s14, 7
	v_lshl_add_u32 v188, s83, 6, v198
	s_lshl_b32 s62, s68, 12
	v_ashrrev_i32_e32 v189, 31, v188
	v_lshl_add_u64 v[184:185], s[62:63], 0, v[188:189]
	v_lshl_or_b32 v210, s16, 2, v196
	v_lshlrev_b64 v[2:3], 10, v[184:185]
	v_lshl_add_u64 v[2:3], s[38:39], 0, v[2:3]
	v_lshlrev_b32_e32 v4, 7, v210
	v_mov_b32_e32 v5, v0
	v_lshl_add_u64 v[2:3], v[2:3], 0, v[4:5]
	v_lshl_add_u64 v[2:3], v[2:3], 0, v[180:181]
	global_load_dwordx4 v[144:147], v[2:3], off
	global_load_dwordx4 v[148:151], v[2:3], off offset:32
	global_load_dwordx4 v[152:155], v[2:3], off offset:64
	global_load_dwordx4 v[156:159], v[2:3], off offset:96
	v_lshlrev_b64 v[252:253], 5, v[184:185]
	v_mul_u32_u24_e32 v254, 3, v210
	v_or_b32_e32 v252, v252, v254
	v_lshl_add_u64 v[252:253], v[252:253], 2, s[92:93]
	global_load_dword v245, v[252:253], off
	global_load_dword v246, v[252:253], off offset:4
	global_load_dword v247, v[252:253], off offset:8
	s_lshl_b32 s4, s68, 19
	s_lshl_b32 s5, s16, 6
	s_or_b32 s4, s4, s5
	s_lshl_b32 s4, s4, 1
	s_add_u32 s14, s45, s4
	s_addc_u32 s15, s46, 0
	s_add_u32 s18, s43, s4
	s_addc_u32 s19, s44, 0
	v_ashrrev_i32_e32 v224, 3, v178
	v_lshl_add_u32 v224, s83, 6, v224
	v_ashrrev_i32_e32 v225, 31, v224
	v_lshlrev_b64 v[224:225], 8, v[224:225]
	v_lshlrev_b32_e32 v254, 4, v178
	v_and_b32_e32 v254, 0x70, v254
	v_or_b32_e32 v224, v224, v254
	v_lshl_add_u64 v[252:253], s[14:15], 0, v[224:225]
	global_load_dwordx4 v[220:223], v[252:253], off
	v_lshl_add_u64 v[252:253], s[18:19], 0, v[224:225]
	global_load_dwordx4 v[248:251], v[252:253], off
	v_lshlrev_b32_e32 v1, 4, v178
	v_mov_b32_e32 v2, v0
	v_mov_b32_e32 v3, v0
	v_mov_b32_e32 v4, v0
	v_mov_b32_e32 v5, v0
	v_add_u32_e32 v6, 0x8000, v1
	ds_write_b128 v1, v[2:5] offset:43008
	ds_write_b128 v1, v[2:5] offset:51200
	ds_write_b128 v1, v[2:5] offset:59392
	ds_write_b128 v6, v[2:5] offset:34816
	v_cmp_gt_u32_e32 vcc, 32, v178
	s_and_saveexec_b64 s[4:5], vcc
	ds_write_b128 v6, v[2:5] offset:43008
